# final rmsnorm phase: norm weights hoisted out of the row loop, row loads merged, per-store vmcnt(0) waits removed
# baseline (speedup 1.0000x reference)
; __device__ __forceinline__ int otid() { int t = threadIdx.x; asm volatile("" : "+v"(t)); return t; }
; __device__ __forceinline__ void phase_final(const Params& p) {
;   const int tid = otid(), lane = tid & 63, wave = tid >> 6;
;   const float* X = (const float*)(p.ws + OFF_X);
;   const float4* nw = (const float4*)p.in[35];
;   for (int it = blockIdx.x; it < NT / 4; it += gridDim.x) {
;     const int row = it * 4 + wave;
;     float* dst;
;     if (row < NTP) {
;       const int b = row / LP, t = row - b * LP;
;       if (t < 16) continue;
;       dst = p.out + O_YP + ((size_t)b * 2048 + (t - 16)) * 1024;
;     } else {
;       dst = p.out + O_YS + (size_t)(row - NTP) * 1024;
;     }
;     const float4* src = (const float4*)(X + (size_t)row * 1024);
;     float4 v[4];
;     float ss = 0.f;
; #pragma unroll
;     for (int i = 0; i < 4; ++i) {
;       v[i] = src[lane + 64 * i];
;       ss += v[i].x * v[i].x + v[i].y * v[i].y + v[i].z * v[i].z + v[i].w * v[i].w;
;     }
;     ss = wave_sum(ss);
;     const float rs = rsqrtf(ss * (1.f / 1024.f) + 1e-6f);
; #pragma unroll
;     for (int i = 0; i < 4; ++i) {
;       const float4 w = nw[lane + 64 * i];
.LBB0_832:
	s_and_b64 vcc, exec, s[12:13]
	s_cbranch_vccz .LBB0_842
	v_readlane_b32 s12, v244, 13
	v_readlane_b32 s13, v244, 14
	v_mov_b32_e32 v0, v178
	s_andn2_b64 vcc, exec, s[12:13]
	s_cbranch_vccnz .LBB0_842
	v_readlane_b32 s12, v244, 9
	v_readlane_b32 s13, v244, 10
	s_load_dword s16, s[12:13], 0x0
	v_and_b32_e32 v8, 63, v0
	v_ashrrev_i32_e32 v6, 6, v0
	v_lshlrev_b32_e32 v2, 4, v8
	v_readlane_b32 s0, v241, 0
	v_lshl_add_u64 v[0:1], s[6:7], 0, v[2:3]
	v_lshl_add_u64 v[4:5], s[10:11], 0, v[2:3]
	v_add_u32_e32 v6, s0, v6
	s_waitcnt lgkmcnt(0)
	s_lshl_b32 s17, s16, 2
	v_lshlrev_b32_e32 v8, 4, v8
	v_readlane_b32 s18, v244, 0
	global_load_dwordx4 v[188:191], v[0:1], off
	global_load_dwordx4 v[192:195], v[0:1], off offset:1024
	global_load_dwordx4 v[196:199], v[0:1], off offset:2048
	global_load_dwordx4 v[200:203], v[0:1], off offset:3072
	s_waitcnt vmcnt(0)
	s_branch .LBB0_836

; __device__ __forceinline__ void phase_final(const Params& p) {
;     ...
;     const int row = it * 4 + wave;
;     float* dst;
;     if (row < NTP) {
;       const int b = row / LP, t = row - b * LP;
;       if (t < 16) continue;
;       dst = p.out + O_YP + ((size_t)b * 2048 + (t - 16)) * 1024;
;     } else {
;       dst = p.out + O_YS + (size_t)(row - NTP) * 1024;
;     }
;     const float4* src = (const float4*)(X + (size_t)row * 1024);
;     float4 v[4];
;     float ss = 0.f;
; #pragma unroll
;     for (int i = 0; i < 4; ++i) {
;       v[i] = src[lane + 64 * i];
;       ss += v[i].x * v[i].x + v[i].y * v[i].y + v[i].z * v[i].z + v[i].w * v[i].w;
;     }
;     ss = wave_sum(ss);
;     const float rs = rsqrtf(ss * (1.f / 1024.f) + 1e-6f);
; #pragma unroll
;     for (int i = 0; i < 4; ++i) {
;       const float4 w = nw[lane + 64 * i];
;       ((float4*)dst)[lane + 64 * i] = make_float4(v[i].x * rs * w.x, v[i].y * rs * w.y, v[i].z * rs * w.z, v[i].w * rs * w.w);
;     }
.LBB0_841:
	v_ashrrev_i32_e32 v7, 31, v6
	v_lshlrev_b64 v[12:13], 12, v[6:7]
	v_lshl_add_u64 v[26:27], v[4:5], 0, v[12:13]
	v_mov_b32_e32 v9, v3
	s_waitcnt vmcnt(4)
	v_lshl_add_u64 v[30:31], v[10:11], 0, v[8:9]
	global_load_dwordx4 v[10:13], v[26:27], off
	global_load_dwordx4 v[18:21], v[26:27], off offset:1024
	global_load_dwordx4 v[204:207], v[26:27], off offset:2048
	global_load_dwordx4 v[208:211], v[26:27], off offset:3072
	v_mov_b32_e32 v14, v188
	v_mov_b32_e32 v15, v189
	v_mov_b32_e32 v16, v190
	v_mov_b32_e32 v17, v191
	s_waitcnt vmcnt(3)
	v_mov_b32_e32 v24, v11
	v_mov_b32_e32 v22, v10
	s_waitcnt vmcnt(2)
	v_mov_b32_e32 v25, v19
	v_mov_b32_e32 v23, v18
	v_pk_mul_f32 v[24:25], v[24:25], v[24:25]
	v_mov_b32_e32 v28, v13
	v_pk_fma_f32 v[22:23], v[22:23], v[22:23], v[24:25]
	v_mov_b32_e32 v24, v12
	v_mov_b32_e32 v25, v20
	v_mov_b32_e32 v29, v21
	v_pk_fma_f32 v[22:23], v[24:25], v[24:25], v[22:23]
	s_nop 0
	v_pk_fma_f32 v[32:33], v[28:29], v[28:29], v[22:23]
	s_nop 0
	v_add_f32_e32 v2, v32, v33
	s_waitcnt vmcnt(1)
	v_mov_b32_e32 v22, v204
	v_mov_b32_e32 v23, v205
	v_mov_b32_e32 v24, v206
	v_mov_b32_e32 v25, v207
	v_mov_b32_e32 v36, v23
	s_waitcnt vmcnt(0)
	v_mov_b32_e32 v26, v208
	v_mov_b32_e32 v27, v209
	v_mov_b32_e32 v28, v210
	v_mov_b32_e32 v29, v211
	v_mov_b32_e32 v37, v27
	v_mov_b32_e32 v34, v22
	v_mov_b32_e32 v35, v26
	v_pk_mul_f32 v[36:37], v[36:37], v[36:37]
	v_mov_b32_e32 v38, v25
	v_pk_fma_f32 v[34:35], v[34:35], v[34:35], v[36:37]
	v_mov_b32_e32 v36, v24
	v_mov_b32_e32 v37, v28
	v_mov_b32_e32 v39, v29
	v_pk_fma_f32 v[34:35], v[36:37], v[36:37], v[34:35]
	s_nop 0
	v_pk_fma_f32 v[34:35], v[38:39], v[38:39], v[34:35]
	s_nop 0
	v_add_f32_e32 v2, v2, v34
	v_add_f32_e32 v2, v2, v35
	s_nop 1
	v_add_f32_dpp v2, v2, v2 quad_perm:[1,0,3,2] row_mask:0xf bank_mask:0xf bound_ctrl:1
	s_nop 1
	v_add_f32_dpp v2, v2, v2 quad_perm:[2,3,0,1] row_mask:0xf bank_mask:0xf bound_ctrl:1
	s_nop 1
	v_add_f32_dpp v2, v2, v2 row_half_mirror row_mask:0xf bank_mask:0xf bound_ctrl:1
	s_nop 1
	v_add_f32_dpp v2, v2, v2 row_mirror row_mask:0xf bank_mask:0xf bound_ctrl:1
	s_nop 0
	v_readlane_b32 s22, v2, 16
	v_readlane_b32 s23, v2, 48
	v_readlane_b32 s14, v2, 0
	v_readlane_b32 s15, v2, 32
	v_mov_b32_e32 v32, s22
	v_mov_b32_e32 v33, s23
	v_pk_add_f32 v[32:33], s[14:15], v[32:33]
	s_nop 0
	v_add_f32_e32 v2, v32, v33
	v_fmamk_f32 v2, v2, 0x3a800000, v180
	v_cmp_gt_f32_e32 vcc, s72, v2
	v_mul_f32_e32 v7, 0x4b800000, v2
	s_nop 0
	v_cndmask_b32_e32 v2, v2, v7, vcc
	v_rsq_f32_e32 v2, v2
	s_nop 0
	v_mul_f32_e32 v7, 0x45800000, v2
	v_cndmask_b32_e32 v2, v2, v7, vcc
	v_pk_mul_f32 v[10:11], v[10:11], v[2:3] op_sel_hi:[1,0]
	v_pk_mul_f32 v[12:13], v[12:13], v[2:3] op_sel_hi:[1,0]
	v_pk_mul_f32 v[10:11], v[14:15], v[10:11]
	v_pk_mul_f32 v[12:13], v[16:17], v[12:13]
	global_store_dwordx4 v[30:31], v[10:13], off
	s_nop 1
	v_mov_b32_e32 v10, v192
	v_mov_b32_e32 v11, v193
	v_mov_b32_e32 v12, v194
	v_mov_b32_e32 v13, v195
	v_pk_mul_f32 v[14:15], v[18:19], v[2:3] op_sel_hi:[1,0]
	v_pk_mul_f32 v[10:11], v[10:11], v[14:15]
	v_pk_mul_f32 v[14:15], v[20:21], v[2:3] op_sel_hi:[1,0]
	s_nop 0
	v_pk_mul_f32 v[12:13], v[12:13], v[14:15]
	global_store_dwordx4 v[30:31], v[10:13], off offset:1024
	s_nop 1
	v_mov_b32_e32 v10, v196
	v_mov_b32_e32 v11, v197
	v_mov_b32_e32 v12, v198
	v_mov_b32_e32 v13, v199
	v_pk_mul_f32 v[14:15], v[22:23], v[2:3] op_sel_hi:[1,0]
	v_pk_mul_f32 v[10:11], v[14:15], v[10:11]
	v_pk_mul_f32 v[14:15], v[24:25], v[2:3] op_sel_hi:[1,0]
	s_nop 0
	v_pk_mul_f32 v[12:13], v[14:15], v[12:13]
	global_store_dwordx4 v[30:31], v[10:13], off offset:2048
	s_nop 1
	v_mov_b32_e32 v10, v200
	v_mov_b32_e32 v11, v201
	v_mov_b32_e32 v12, v202
	v_mov_b32_e32 v13, v203
	v_pk_mul_f32 v[14:15], v[26:27], v[2:3] op_sel_hi:[1,0]
	v_pk_mul_f32 v[10:11], v[14:15], v[10:11]
	v_pk_mul_f32 v[14:15], v[28:29], v[2:3] op_sel_hi:[1,0]
	s_nop 0
	v_pk_mul_f32 v[12:13], v[14:15], v[12:13]
	global_store_dwordx4 v[30:31], v[10:13], off offset:3072
	s_branch .LBB0_835
